# NSA selected-block loop: row-sum chain and bf16 packing moved into the P.V MFMA gaps with V fragments prefetched ahead (on top of MLA P.V-shadow schedule)
# baseline (speedup 1.0000x reference)
; __device__ __forceinline__ float fast_exp2(float x) { return __builtin_amdgcn_exp2f(x); }
; __device__ __forceinline__ float xhalf_max(float x) { auto rr = __builtin_amdgcn_permlane32_swap(__float_as_uint(x), __float_as_uint(x), false, false); return fmaxf(__uint_as_float(rr[0]), __uint_as_float(rr[1])); }
; template <int D, int DV, int MODE, bool HASBIAS, bool JOINT, bool DEFER, class KA, class VA, class PF, class BF, class VF, class NM, class WS, class CB> ...
;     ...
;                     float mx0 = fmaxf(fmaxf(s[0], s[1]), s[2]), mx1 = fmaxf(fmaxf(s[3], s[4]), s[5]);
;                     mx0 = fmaxf(fmaxf(mx0, s[6]), s[7]); mx1 = fmaxf(fmaxf(mx1, s[8]), s[9]); mx0 = fmaxf(fmaxf(mx0, s[10]), s[11]); mx1 = fmaxf(fmaxf(mx1, s[12]), s[13]);
;                     float mx = fmaxf(fmaxf(mx0, mx1), fmaxf(s[14], s[15]));
;                     mx = xhalf_max(mx);
;                     const bool grow = __any(mx > m + RESC_THR);
;                     const float mn = grow ? fmaxf(m, mx) : m; float sum = 0.f;
;                     if (masked) {
; #pragma unroll
;                         for (int v = 0; v < 16; ++v) { const float p = s[v] > -1e29f ? fast_exp2(s[v] - mn) : 0.f; s[v] = p; sum += p; }
;                     } else {
; #pragma unroll
;                         for (int v = 0; v < 16; ++v) { const float p = fast_exp2(s[v] - mn); s[v] = p; sum += p; }
;                     }
.LBB0_807:
	v_max3_f32 v1, v100, v101, v98
	v_max3_f32 v2, v99, v96, v97
	v_max3_f32 v1, v1, v94, v95
	v_max3_f32 v2, v2, v92, v93
	v_max_f32_e32 v36, v51, v51
	v_max_f32_e32 v37, v50, v50
	v_max3_f32 v1, v1, v90, v91
	v_max3_f32 v2, v2, v88, v89
	v_max_f32_e32 v36, v37, v36
	v_max3_f32 v1, v1, v2, v36
	v_mov_b32_e32 v2, v1
	s_nop 1
	v_permlane32_swap_b32_e32 v1, v2
	v_max_f32_e32 v2, v2, v2
	v_max_f32_e32 v1, v1, v1
	v_max_f32_e32 v1, v1, v2
	v_add_f32_e32 v2, 0x40c00000, v222
	v_cmp_gt_f32_e32 vcc, v1, v2
	s_cmp_lg_u64 vcc, 0
	s_cselect_b64 s[8:9], -1, 0
	s_cmp_eq_u64 vcc, 0
	v_max_f32_e32 v2, v222, v222
	s_cselect_b64 vcc, -1, 0
	v_max_f32_e32 v102, v2, v1
	v_cndmask_b32_e32 v223, v102, v222, vcc
	v_sub_f32_e32 v1, v100, v223
	v_sub_f32_e32 v2, v101, v223
	v_sub_f32_e32 v36, v98, v223
	v_sub_f32_e32 v37, v99, v223
	v_sub_f32_e32 v38, v96, v223
	v_sub_f32_e32 v39, v97, v223
	v_sub_f32_e32 v40, v94, v223
	v_sub_f32_e32 v41, v95, v223
	v_sub_f32_e32 v42, v92, v223
	v_sub_f32_e32 v43, v93, v223
	v_sub_f32_e32 v103, v90, v223
	v_sub_f32_e32 v160, v91, v223
	v_sub_f32_e32 v161, v88, v223
	v_sub_f32_e32 v176, v89, v223
	v_sub_f32_e32 v177, v50, v223
	v_sub_f32_e32 v178, v51, v223
	v_exp_f32_e32 v48, v1
	v_exp_f32_e32 v1, v2
	v_exp_f32_e32 v2, v36
	v_exp_f32_e32 v49, v37
	v_exp_f32_e32 v46, v38
	v_exp_f32_e32 v47, v39
	v_exp_f32_e32 v44, v40
	v_exp_f32_e32 v45, v41
	v_exp_f32_e32 v42, v42
	v_exp_f32_e32 v43, v43
	v_exp_f32_e32 v40, v103
	v_exp_f32_e32 v41, v160
	v_exp_f32_e32 v38, v161
	v_exp_f32_e32 v39, v176
	v_exp_f32_e32 v36, v177
	v_exp_f32_e32 v37, v178
	s_mov_b64 s[16:17], -1
	s_andn2_b64 vcc, exec, s[10:11]
	s_cbranch_vccnz .LBB0_812
.Lnsa_sum1:
	s_cbranch_execz .LBB0_813
.LBB0_809:
	s_andn2_b64 vcc, exec, s[8:9]
	s_cbranch_vccnz .LBB0_811

; __device__ __forceinline__ unsigned cvt_pk_bf16(float lo, float hi) { unsigned r; asm volatile("v_cvt_pk_bf16_f32 %0, %1, %2" : "=v"(r) : "v"(lo), "v"(hi)); return r; }
; #define LAS __attribute__((address_space(3)))
; template <int DV32>
; __device__ __forceinline__ void pv_sub(f32x16 (&o)[DV32], const LAS unsigned char* Vt, int vs, int sub, const f32x16& p, int r32, int hi) {
;     ...
;     for (int kb = 0; kb < 2; ++kb) {
;         u32x4 pw; pw.x = cvt_pk_bf16(p[8 * kb + 0], p[8 * kb + 1]); pw.y = cvt_pk_bf16(p[8 * kb + 2], p[8 * kb + 3]); pw.z = cvt_pk_bf16(p[8 * kb + 4], p[8 * kb + 5]); pw.w = cvt_pk_bf16(p[8 * kb + 6], p[8 * kb + 7]);
;         const bf16x8 pf = __builtin_bit_cast(bf16x8, pw);
; #pragma unroll
;         for (int i = 0; i < DV32; ++i) {
;             const bf16x8 vf = *(const LAS bf16x8*)(Vt + (32 * i + r32) * vs + sub * 64 + kb * 32 + hi * 16);
;             o[i] = __builtin_amdgcn_mfma_f32_32x32x16_bf16(vf, pf, o[i], 0, 0, 0);
;         }
; template <int D, int DV, int MODE, bool HASBIAS, bool JOINT, bool DEFER, class KA, class VA, class PF, class BF, class VF, class NM, class WS, class CB> ...
;     ...
;                     l += sum; m = mn;
;                     if (MODE == 0) pv_sub<DV / 32>(o, curv, VS, sub, s, r32, hi);
.LBB0_811:
	v_add_u32_e32 v50, v167, v164
	v_cvt_pk_bf16_f32 v88, v48, v1
	v_cvt_pk_bf16_f32 v89, v2, v49
	ds_read_b128 v[96:99], v50 offset:18432
	ds_read_b128 v[176:179], v50 offset:23040
	v_cvt_pk_bf16_f32 v90, v46, v47
	v_cvt_pk_bf16_f32 v91, v44, v45
	v_add_f32_e32 v103, 0, v48
	v_add_f32_e32 v103, v1, v103
	v_add_f32_e32 v103, v2, v103
	v_add_f32_e32 v103, v49, v103
	s_waitcnt lgkmcnt(1)
	v_mfma_f32_32x32x16_bf16 v[4:19], v[96:99], v[88:91], v[4:19]
	ds_read_b128 v[96:99], v50 offset:18464
	v_cvt_pk_bf16_f32 v92, v42, v43
	v_cvt_pk_bf16_f32 v93, v40, v41
	v_add_f32_e32 v103, v46, v103
	v_add_f32_e32 v103, v47, v103
	v_add_f32_e32 v103, v44, v103
	v_add_f32_e32 v103, v45, v103
	s_waitcnt lgkmcnt(1)
	v_mfma_f32_32x32x16_bf16 v[20:35], v[176:179], v[88:91], v[20:35]
	ds_read_b128 v[176:179], v50 offset:23072
	v_cvt_pk_bf16_f32 v94, v38, v39
	v_cvt_pk_bf16_f32 v95, v36, v37
	v_add_f32_e32 v103, v42, v103
	v_add_f32_e32 v103, v43, v103
	v_add_f32_e32 v103, v40, v103
	v_add_f32_e32 v103, v41, v103
	s_waitcnt lgkmcnt(1)
	v_mfma_f32_32x32x16_bf16 v[4:19], v[96:99], v[92:95], v[4:19]
	v_mov_b32_e32 v1, s30
	ds_read_b32 v1, v1
	v_add_f32_e32 v103, v38, v103
	v_add_f32_e32 v103, v39, v103
	v_add_f32_e32 v103, v36, v103
	v_add_f32_e32 v103, v37, v103
	v_add_f32_e32 v221, v103, v221
	s_waitcnt lgkmcnt(0)
	v_readfirstlane_b32 s12, v1
	v_mfma_f32_32x32x16_bf16 v[20:35], v[176:179], v[92:95], v[20:35]
	v_lshlrev_b64 v[160:161], v1, 1
	s_branch .LBB0_815

; __device__ __forceinline__ float fast_exp2(float x) { return __builtin_amdgcn_exp2f(x); }
; template <int D, int DV, int MODE, bool HASBIAS, bool JOINT, bool DEFER, class KA, class VA, class PF, class BF, class VF, class NM, class WS, class CB> ...
;     ...
;                     if (masked) {
; #pragma unroll
;                         for (int v = 0; v < 16; ++v) { const float p = s[v] > -1e29f ? fast_exp2(s[v] - mn) : 0.f; s[v] = p; sum += p; }
.LBB0_813:
	s_cmp_lg_u32 s12, s61
	s_cbranch_scc1 .Lnsa_fs1
	s_mov_b32 s10, 0xefa18f08
	v_cmp_lt_f32_e32 vcc, s10, v100
	s_nop 1
	v_cndmask_b32_e32 v48, 0, v48, vcc
	v_cmp_lt_f32_e32 vcc, s10, v101
	s_nop 1
	v_cndmask_b32_e32 v1, 0, v1, vcc
	v_cmp_lt_f32_e32 vcc, s10, v98
	s_nop 1
	v_cndmask_b32_e32 v2, 0, v2, vcc
	v_cmp_lt_f32_e32 vcc, s10, v99
	s_nop 1
	v_cndmask_b32_e32 v49, 0, v49, vcc
	v_cmp_lt_f32_e32 vcc, s10, v96
	s_nop 1
	v_cndmask_b32_e32 v46, 0, v46, vcc
	v_cmp_lt_f32_e32 vcc, s10, v97
	s_nop 1
	v_cndmask_b32_e32 v47, 0, v47, vcc
	v_cmp_lt_f32_e32 vcc, s10, v94
	s_nop 1
	v_cndmask_b32_e32 v44, 0, v44, vcc
	v_cmp_lt_f32_e32 vcc, s10, v95
	s_nop 1
	v_cndmask_b32_e32 v45, 0, v45, vcc
	v_cmp_lt_f32_e32 vcc, s10, v92
	s_nop 1
	v_cndmask_b32_e32 v42, 0, v42, vcc
	v_cmp_lt_f32_e32 vcc, s10, v93
	s_nop 1
	v_cndmask_b32_e32 v43, 0, v43, vcc
	v_cmp_lt_f32_e32 vcc, s10, v90
	s_nop 1
	v_cndmask_b32_e32 v40, 0, v40, vcc
	v_cmp_lt_f32_e32 vcc, s10, v91
	s_nop 1
	v_cndmask_b32_e32 v41, 0, v41, vcc
	v_cmp_lt_f32_e32 vcc, s10, v88
	s_nop 1
	v_cndmask_b32_e32 v38, 0, v38, vcc
	v_cmp_lt_f32_e32 vcc, s10, v89
	s_nop 1
	v_cndmask_b32_e32 v39, 0, v39, vcc
	v_cmp_lt_f32_e32 vcc, s10, v50
	s_nop 1
	v_cndmask_b32_e32 v36, 0, v36, vcc
	v_cmp_lt_f32_e32 vcc, s10, v51
	s_nop 1
	v_cndmask_b32_e32 v37, 0, v37, vcc
	s_andn2_b64 vcc, exec, s[8:9]
	s_cbranch_vccz .LBB0_810
	s_branch .LBB0_811

; __device__ __forceinline__ float fast_exp2(float x) { return __builtin_amdgcn_exp2f(x); }
; __device__ __forceinline__ float xhalf_max(float x) { auto rr = __builtin_amdgcn_permlane32_swap(__float_as_uint(x), __float_as_uint(x), false, false); return fmaxf(__uint_as_float(rr[0]), __uint_as_float(rr[1])); }
; template <int D, int DV, int MODE, bool HASBIAS, bool JOINT, bool DEFER, class KA, class VA, class PF, class BF, class VF, class NM, class WS, class CB> ...
;     ...
;                     float mx0 = fmaxf(fmaxf(s[0], s[1]), s[2]), mx1 = fmaxf(fmaxf(s[3], s[4]), s[5]);
;                     mx0 = fmaxf(fmaxf(mx0, s[6]), s[7]); mx1 = fmaxf(fmaxf(mx1, s[8]), s[9]); mx0 = fmaxf(fmaxf(mx0, s[10]), s[11]); mx1 = fmaxf(fmaxf(mx1, s[12]), s[13]);
;                     float mx = fmaxf(fmaxf(mx0, mx1), fmaxf(s[14], s[15]));
;                     mx = xhalf_max(mx);
;                     const bool grow = __any(mx > m + RESC_THR);
;                     const float mn = grow ? fmaxf(m, mx) : m; float sum = 0.f;
;                     if (masked) {
; #pragma unroll
;                         for (int v = 0; v < 16; ++v) { const float p = s[v] > -1e29f ? fast_exp2(s[v] - mn) : 0.f; s[v] = p; sum += p; }
;                     } else {
; #pragma unroll
;                         for (int v = 0; v < 16; ++v) { const float p = fast_exp2(s[v] - mn); s[v] = p; sum += p; }
;                     }
.LBB0_820:
	v_max3_f32 v1, v100, v101, v98
	v_max3_f32 v2, v99, v96, v97
	v_max3_f32 v1, v1, v94, v95
	v_max3_f32 v2, v2, v92, v93
	v_max_f32_e32 v36, v51, v51
	v_max_f32_e32 v37, v50, v50
	v_max3_f32 v1, v1, v90, v91
	v_max3_f32 v2, v2, v88, v89
	v_max_f32_e32 v36, v37, v36
	v_max3_f32 v1, v1, v2, v36
	v_mov_b32_e32 v2, v1
	s_nop 1
	v_permlane32_swap_b32_e32 v1, v2
	v_max_f32_e32 v2, v2, v2
	v_max_f32_e32 v1, v1, v1
	v_max_f32_e32 v1, v1, v2
	v_add_f32_e32 v2, 0x40c00000, v223
	v_cmp_gt_f32_e32 vcc, v1, v2
	s_cmp_lg_u64 vcc, 0
	s_cselect_b64 s[8:9], -1, 0
	s_cmp_eq_u64 vcc, 0
	v_max_f32_e32 v2, v223, v223
	s_cselect_b64 vcc, -1, 0
	v_max_f32_e32 v102, v2, v1
	v_cndmask_b32_e32 v222, v102, v223, vcc
	v_sub_f32_e32 v1, v100, v222
	v_sub_f32_e32 v2, v101, v222
	v_sub_f32_e32 v36, v98, v222
	v_sub_f32_e32 v37, v99, v222
	v_sub_f32_e32 v38, v96, v222
	v_sub_f32_e32 v39, v97, v222
	v_sub_f32_e32 v40, v94, v222
	v_sub_f32_e32 v41, v95, v222
	v_sub_f32_e32 v42, v92, v222
	v_sub_f32_e32 v43, v93, v222
	v_sub_f32_e32 v103, v90, v222
	v_sub_f32_e32 v160, v91, v222
	v_sub_f32_e32 v161, v88, v222
	v_sub_f32_e32 v176, v89, v222
	v_sub_f32_e32 v177, v50, v222
	v_sub_f32_e32 v178, v51, v222
	v_exp_f32_e32 v48, v1
	v_exp_f32_e32 v1, v2
	v_exp_f32_e32 v2, v36
	v_exp_f32_e32 v49, v37
	v_exp_f32_e32 v46, v38
	v_exp_f32_e32 v47, v39
	v_exp_f32_e32 v44, v40
	v_exp_f32_e32 v45, v41
	v_exp_f32_e32 v42, v42
	v_exp_f32_e32 v43, v43
	v_exp_f32_e32 v40, v103
	v_exp_f32_e32 v41, v160
	v_exp_f32_e32 v38, v161
	v_exp_f32_e32 v39, v176
	v_exp_f32_e32 v36, v177
	v_exp_f32_e32 v37, v178
	s_mov_b64 s[16:17], -1
	s_andn2_b64 vcc, exec, s[10:11]
	s_cbranch_vccnz .LBB0_825
.Lnsa_sum2:
	s_cbranch_execz .LBB0_826
.LBB0_822:
	s_andn2_b64 vcc, exec, s[8:9]
	s_cbranch_vccnz .LBB0_824

; __device__ __forceinline__ unsigned cvt_pk_bf16(float lo, float hi) { unsigned r; asm volatile("v_cvt_pk_bf16_f32 %0, %1, %2" : "=v"(r) : "v"(lo), "v"(hi)); return r; }
; #define LAS __attribute__((address_space(3)))
; template <int DV32>
; __device__ __forceinline__ void pv_sub(f32x16 (&o)[DV32], const LAS unsigned char* Vt, int vs, int sub, const f32x16& p, int r32, int hi) {
;     ...
;     for (int kb = 0; kb < 2; ++kb) {
;         u32x4 pw; pw.x = cvt_pk_bf16(p[8 * kb + 0], p[8 * kb + 1]); pw.y = cvt_pk_bf16(p[8 * kb + 2], p[8 * kb + 3]); pw.z = cvt_pk_bf16(p[8 * kb + 4], p[8 * kb + 5]); pw.w = cvt_pk_bf16(p[8 * kb + 6], p[8 * kb + 7]);
;         const bf16x8 pf = __builtin_bit_cast(bf16x8, pw);
; #pragma unroll
;         for (int i = 0; i < DV32; ++i) {
;             const bf16x8 vf = *(const LAS bf16x8*)(Vt + (32 * i + r32) * vs + sub * 64 + kb * 32 + hi * 16);
;             o[i] = __builtin_amdgcn_mfma_f32_32x32x16_bf16(vf, pf, o[i], 0, 0, 0);
;         }
; template <int D, int DV, int MODE, bool HASBIAS, bool JOINT, bool DEFER, class KA, class VA, class PF, class BF, class VF, class NM, class WS, class CB> ...
;     ...
;                     l += sum; m = mn;
;                     if (MODE == 0) pv_sub<DV / 32>(o, curv, VS, sub, s, r32, hi);
.LBB0_824:
	v_add_u32_e32 v50, v167, v164
	v_cvt_pk_bf16_f32 v88, v48, v1
	v_cvt_pk_bf16_f32 v89, v2, v49
	ds_read_b128 v[96:99], v50 offset:18496
	ds_read_b128 v[176:179], v50 offset:23104
	v_cvt_pk_bf16_f32 v90, v46, v47
	v_cvt_pk_bf16_f32 v91, v44, v45
	v_add_f32_e32 v103, 0, v48
	v_add_f32_e32 v103, v1, v103
	v_add_f32_e32 v103, v2, v103
	v_add_f32_e32 v103, v49, v103
	s_waitcnt lgkmcnt(1)
	v_mfma_f32_32x32x16_bf16 v[4:19], v[96:99], v[88:91], v[4:19]
	ds_read_b128 v[96:99], v50 offset:18528
	v_cvt_pk_bf16_f32 v92, v42, v43
	v_cvt_pk_bf16_f32 v93, v40, v41
	v_add_f32_e32 v103, v46, v103
	v_add_f32_e32 v103, v47, v103
	v_add_f32_e32 v103, v44, v103
	v_add_f32_e32 v103, v45, v103
	s_waitcnt lgkmcnt(1)
	v_mfma_f32_32x32x16_bf16 v[20:35], v[176:179], v[88:91], v[20:35]
	ds_read_b128 v[176:179], v50 offset:23136
	v_cvt_pk_bf16_f32 v94, v38, v39
	v_cvt_pk_bf16_f32 v95, v36, v37
	v_add_f32_e32 v103, v42, v103
	v_add_f32_e32 v103, v43, v103
	v_add_f32_e32 v103, v40, v103
	v_add_f32_e32 v103, v41, v103
	s_waitcnt lgkmcnt(1)
	v_mfma_f32_32x32x16_bf16 v[4:19], v[96:99], v[92:95], v[4:19]
	v_add_f32_e32 v103, v38, v103
	v_add_f32_e32 v103, v39, v103
	v_add_f32_e32 v103, v36, v103
	v_add_f32_e32 v103, v37, v103
	v_add_f32_e32 v221, v103, v221
	s_waitcnt lgkmcnt(0)
	v_mfma_f32_32x32x16_bf16 v[20:35], v[176:179], v[92:95], v[20:35]
	s_branch .LBB0_828

; __device__ __forceinline__ float fast_exp2(float x) { return __builtin_amdgcn_exp2f(x); }
; __device__ __forceinline__ float xhalf_max(float x) { auto rr = __builtin_amdgcn_permlane32_swap(__float_as_uint(x), __float_as_uint(x), false, false); return fmaxf(__uint_as_float(rr[0]), __uint_as_float(rr[1])); }
; template <int D, int DV, int MODE, bool HASBIAS, bool JOINT, bool DEFER, class KA, class VA, class PF, class BF, class VF, class NM, class WS, class CB> ...
;     ...
;                     float mx0 = fmaxf(fmaxf(s[0], s[1]), s[2]), mx1 = fmaxf(fmaxf(s[3], s[4]), s[5]);
;                     mx0 = fmaxf(fmaxf(mx0, s[6]), s[7]); mx1 = fmaxf(fmaxf(mx1, s[8]), s[9]); mx0 = fmaxf(fmaxf(mx0, s[10]), s[11]); mx1 = fmaxf(fmaxf(mx1, s[12]), s[13]);
;                     float mx = fmaxf(fmaxf(mx0, mx1), fmaxf(s[14], s[15]));
;                     mx = xhalf_max(mx);
;                     const bool grow = __any(mx > m + RESC_THR);
;                     const float mn = grow ? fmaxf(m, mx) : m; float sum = 0.f;
;                     if (masked) {
; #pragma unroll
;                         for (int v = 0; v < 16; ++v) { const float p = s[v] > -1e29f ? fast_exp2(s[v] - mn) : 0.f; s[v] = p; sum += p; }
;                     } else {
; #pragma unroll
;                         for (int v = 0; v < 16; ++v) { const float p = fast_exp2(s[v] - mn); s[v] = p; sum += p; }
;                     }
.LBB0_846:
	v_max3_f32 v1, v100, v101, v98
	v_max3_f32 v2, v99, v96, v97
	v_max3_f32 v1, v1, v94, v95
	v_max3_f32 v2, v2, v92, v93
	v_max_f32_e32 v36, v51, v51
	v_max_f32_e32 v37, v50, v50
	v_max3_f32 v1, v1, v90, v91
	v_max3_f32 v2, v2, v88, v89
	v_max_f32_e32 v36, v37, v36
	v_max3_f32 v1, v1, v2, v36
	v_mov_b32_e32 v2, v1
	s_nop 1
	v_permlane32_swap_b32_e32 v1, v2
	v_max_f32_e32 v2, v2, v2
	v_max_f32_e32 v1, v1, v1
	v_max_f32_e32 v1, v1, v2
	v_add_f32_e32 v2, 0x40c00000, v222
	v_cmp_gt_f32_e32 vcc, v1, v2
	s_cmp_lg_u64 vcc, 0
	s_cselect_b64 s[8:9], -1, 0
	s_cmp_eq_u64 vcc, 0
	v_max_f32_e32 v2, v222, v222
	s_cselect_b64 vcc, -1, 0
	v_max_f32_e32 v102, v2, v1
	v_cndmask_b32_e32 v223, v102, v222, vcc
	v_sub_f32_e32 v1, v100, v223
	v_sub_f32_e32 v2, v101, v223
	v_sub_f32_e32 v36, v98, v223
	v_sub_f32_e32 v37, v99, v223
	v_sub_f32_e32 v38, v96, v223
	v_sub_f32_e32 v39, v97, v223
	v_sub_f32_e32 v40, v94, v223
	v_sub_f32_e32 v41, v95, v223
	v_sub_f32_e32 v42, v92, v223
	v_sub_f32_e32 v43, v93, v223
	v_sub_f32_e32 v103, v90, v223
	v_sub_f32_e32 v160, v91, v223
	v_sub_f32_e32 v161, v88, v223
	v_sub_f32_e32 v176, v89, v223
	v_sub_f32_e32 v177, v50, v223
	v_sub_f32_e32 v178, v51, v223
	v_exp_f32_e32 v48, v1
	v_exp_f32_e32 v1, v2
	v_exp_f32_e32 v2, v36
	v_exp_f32_e32 v49, v37
	v_exp_f32_e32 v46, v38
	v_exp_f32_e32 v47, v39
	v_exp_f32_e32 v44, v40
	v_exp_f32_e32 v45, v41
	v_exp_f32_e32 v42, v42
	v_exp_f32_e32 v43, v43
	v_exp_f32_e32 v40, v103
	v_exp_f32_e32 v41, v160
	v_exp_f32_e32 v38, v161
	v_exp_f32_e32 v39, v176
	v_exp_f32_e32 v36, v177
	v_exp_f32_e32 v37, v178
	s_mov_b64 s[16:17], -1
	s_andn2_b64 vcc, exec, s[10:11]
	s_cbranch_vccnz .LBB0_851
.Lnsa_sum3:
	s_cbranch_execz .LBB0_852
.LBB0_848:
	s_andn2_b64 vcc, exec, s[8:9]
	s_cbranch_vccnz .LBB0_850

; __device__ __forceinline__ unsigned cvt_pk_bf16(float lo, float hi) { unsigned r; asm volatile("v_cvt_pk_bf16_f32 %0, %1, %2" : "=v"(r) : "v"(lo), "v"(hi)); return r; }
; #define LAS __attribute__((address_space(3)))
; template <int DV32>
; __device__ __forceinline__ void pv_sub(f32x16 (&o)[DV32], const LAS unsigned char* Vt, int vs, int sub, const f32x16& p, int r32, int hi) {
;     ...
;     for (int kb = 0; kb < 2; ++kb) {
;         u32x4 pw; pw.x = cvt_pk_bf16(p[8 * kb + 0], p[8 * kb + 1]); pw.y = cvt_pk_bf16(p[8 * kb + 2], p[8 * kb + 3]); pw.z = cvt_pk_bf16(p[8 * kb + 4], p[8 * kb + 5]); pw.w = cvt_pk_bf16(p[8 * kb + 6], p[8 * kb + 7]);
;         const bf16x8 pf = __builtin_bit_cast(bf16x8, pw);
; #pragma unroll
;         for (int i = 0; i < DV32; ++i) {
;             const bf16x8 vf = *(const LAS bf16x8*)(Vt + (32 * i + r32) * vs + sub * 64 + kb * 32 + hi * 16);
;             o[i] = __builtin_amdgcn_mfma_f32_32x32x16_bf16(vf, pf, o[i], 0, 0, 0);
;         }
; template <int D, int DV, int MODE, bool HASBIAS, bool JOINT, bool DEFER, class KA, class VA, class PF, class BF, class VF, class NM, class WS, class CB> ...
;     ...
;                     l += sum; m = mn;
;                     if (MODE == 0) pv_sub<DV / 32>(o, curv, VS, sub, s, r32, hi);
.LBB0_850:
	v_add_u32_e32 v50, v167, v164
	v_cvt_pk_bf16_f32 v88, v48, v1
	v_cvt_pk_bf16_f32 v89, v2, v49
	ds_read_b128 v[96:99], v50 offset:27648
	ds_read_b128 v[176:179], v50 offset:32256
	v_cvt_pk_bf16_f32 v90, v46, v47
	v_cvt_pk_bf16_f32 v91, v44, v45
	v_add_f32_e32 v103, 0, v48
	v_add_f32_e32 v103, v1, v103
	v_add_f32_e32 v103, v2, v103
	v_add_f32_e32 v103, v49, v103
	s_waitcnt lgkmcnt(1)
	v_mfma_f32_32x32x16_bf16 v[4:19], v[96:99], v[88:91], v[4:19]
	ds_read_b128 v[96:99], v50 offset:27680
	v_cvt_pk_bf16_f32 v92, v42, v43
	v_cvt_pk_bf16_f32 v93, v40, v41
	v_add_f32_e32 v103, v46, v103
	v_add_f32_e32 v103, v47, v103
	v_add_f32_e32 v103, v44, v103
	v_add_f32_e32 v103, v45, v103
	s_waitcnt lgkmcnt(1)
	v_mfma_f32_32x32x16_bf16 v[20:35], v[176:179], v[88:91], v[20:35]
	ds_read_b128 v[176:179], v50 offset:32288
	v_cvt_pk_bf16_f32 v94, v38, v39
	v_cvt_pk_bf16_f32 v95, v36, v37
	v_add_f32_e32 v103, v42, v103
	v_add_f32_e32 v103, v43, v103
	v_add_f32_e32 v103, v40, v103
	v_add_f32_e32 v103, v41, v103
	s_waitcnt lgkmcnt(1)
	v_mfma_f32_32x32x16_bf16 v[4:19], v[96:99], v[92:95], v[4:19]
	v_mov_b32_e32 v1, s30
	ds_read_b32 v1, v1 offset:4
	v_add_f32_e32 v103, v38, v103
	v_add_f32_e32 v103, v39, v103
	v_add_f32_e32 v103, v36, v103
	v_add_f32_e32 v103, v37, v103
	v_add_f32_e32 v221, v103, v221
	s_waitcnt lgkmcnt(0)
	v_readfirstlane_b32 s12, v1
	v_mfma_f32_32x32x16_bf16 v[20:35], v[176:179], v[92:95], v[20:35]
	v_lshlrev_b64 v[160:161], v1, 1
	s_branch .LBB0_854

; __device__ __forceinline__ float fast_exp2(float x) { return __builtin_amdgcn_exp2f(x); }
; __device__ __forceinline__ float xhalf_max(float x) { auto rr = __builtin_amdgcn_permlane32_swap(__float_as_uint(x), __float_as_uint(x), false, false); return fmaxf(__uint_as_float(rr[0]), __uint_as_float(rr[1])); }
; template <int D, int DV, int MODE, bool HASBIAS, bool JOINT, bool DEFER, class KA, class VA, class PF, class BF, class VF, class NM, class WS, class CB> ...
;     ...
;                     float mx0 = fmaxf(fmaxf(s[0], s[1]), s[2]), mx1 = fmaxf(fmaxf(s[3], s[4]), s[5]);
;                     mx0 = fmaxf(fmaxf(mx0, s[6]), s[7]); mx1 = fmaxf(fmaxf(mx1, s[8]), s[9]); mx0 = fmaxf(fmaxf(mx0, s[10]), s[11]); mx1 = fmaxf(fmaxf(mx1, s[12]), s[13]);
;                     float mx = fmaxf(fmaxf(mx0, mx1), fmaxf(s[14], s[15]));
;                     mx = xhalf_max(mx);
;                     const bool grow = __any(mx > m + RESC_THR);
;                     const float mn = grow ? fmaxf(m, mx) : m; float sum = 0.f;
;                     if (masked) {
; #pragma unroll
;                         for (int v = 0; v < 16; ++v) { const float p = s[v] > -1e29f ? fast_exp2(s[v] - mn) : 0.f; s[v] = p; sum += p; }
;                     } else {
; #pragma unroll
;                         for (int v = 0; v < 16; ++v) { const float p = fast_exp2(s[v] - mn); s[v] = p; sum += p; }
;                     }
.LBB0_859:
	v_max3_f32 v1, v100, v101, v98
	v_max3_f32 v2, v99, v96, v97
	v_max3_f32 v1, v1, v94, v95
	v_max3_f32 v2, v2, v92, v93
	v_max_f32_e32 v36, v51, v51
	v_max_f32_e32 v37, v50, v50
	v_max3_f32 v1, v1, v90, v91
	v_max3_f32 v2, v2, v88, v89
	v_max_f32_e32 v36, v37, v36
	v_max3_f32 v1, v1, v2, v36
	v_mov_b32_e32 v2, v1
	s_nop 1
	v_permlane32_swap_b32_e32 v1, v2
	v_max_f32_e32 v2, v2, v2
	v_max_f32_e32 v1, v1, v1
	v_max_f32_e32 v1, v1, v2
	v_add_f32_e32 v2, 0x40c00000, v223
	v_cmp_gt_f32_e32 vcc, v1, v2
	s_cmp_lg_u64 vcc, 0
	s_cselect_b64 s[8:9], -1, 0
	s_cmp_eq_u64 vcc, 0
	v_max_f32_e32 v2, v223, v223
	s_cselect_b64 vcc, -1, 0
	v_max_f32_e32 v102, v2, v1
	v_cndmask_b32_e32 v222, v102, v223, vcc
	v_sub_f32_e32 v1, v100, v222
	v_sub_f32_e32 v2, v101, v222
	v_sub_f32_e32 v36, v98, v222
	v_sub_f32_e32 v37, v99, v222
	v_sub_f32_e32 v38, v96, v222
	v_sub_f32_e32 v39, v97, v222
	v_sub_f32_e32 v40, v94, v222
	v_sub_f32_e32 v41, v95, v222
	v_sub_f32_e32 v42, v92, v222
	v_sub_f32_e32 v43, v93, v222
	v_sub_f32_e32 v103, v90, v222
	v_sub_f32_e32 v160, v91, v222
	v_sub_f32_e32 v161, v88, v222
	v_sub_f32_e32 v176, v89, v222
	v_sub_f32_e32 v177, v50, v222
	v_sub_f32_e32 v178, v51, v222
	v_exp_f32_e32 v48, v1
	v_exp_f32_e32 v1, v2
	v_exp_f32_e32 v2, v36
	v_exp_f32_e32 v49, v37
	v_exp_f32_e32 v46, v38
	v_exp_f32_e32 v47, v39
	v_exp_f32_e32 v44, v40
	v_exp_f32_e32 v45, v41
	v_exp_f32_e32 v42, v42
	v_exp_f32_e32 v43, v43
	v_exp_f32_e32 v40, v103
	v_exp_f32_e32 v41, v160
	v_exp_f32_e32 v38, v161
	v_exp_f32_e32 v39, v176
	v_exp_f32_e32 v36, v177
	v_exp_f32_e32 v37, v178
	s_mov_b64 s[16:17], -1
	s_andn2_b64 vcc, exec, s[10:11]
	s_cbranch_vccnz .LBB0_864
.Lnsa_sum4:
	s_cbranch_execz .LBB0_865
.LBB0_861:
	s_andn2_b64 vcc, exec, s[8:9]
	s_cbranch_vccnz .LBB0_863

; __device__ __forceinline__ unsigned cvt_pk_bf16(float lo, float hi) { unsigned r; asm volatile("v_cvt_pk_bf16_f32 %0, %1, %2" : "=v"(r) : "v"(lo), "v"(hi)); return r; }
; #define LAS __attribute__((address_space(3)))
; template <int DV32>
; __device__ __forceinline__ void pv_sub(f32x16 (&o)[DV32], const LAS unsigned char* Vt, int vs, int sub, const f32x16& p, int r32, int hi) {
;     ...
;     for (int kb = 0; kb < 2; ++kb) {
;         u32x4 pw; pw.x = cvt_pk_bf16(p[8 * kb + 0], p[8 * kb + 1]); pw.y = cvt_pk_bf16(p[8 * kb + 2], p[8 * kb + 3]); pw.z = cvt_pk_bf16(p[8 * kb + 4], p[8 * kb + 5]); pw.w = cvt_pk_bf16(p[8 * kb + 6], p[8 * kb + 7]);
;         const bf16x8 pf = __builtin_bit_cast(bf16x8, pw);
; #pragma unroll
;         for (int i = 0; i < DV32; ++i) {
;             const bf16x8 vf = *(const LAS bf16x8*)(Vt + (32 * i + r32) * vs + sub * 64 + kb * 32 + hi * 16);
;             o[i] = __builtin_amdgcn_mfma_f32_32x32x16_bf16(vf, pf, o[i], 0, 0, 0);
;         }
; template <int D, int DV, int MODE, bool HASBIAS, bool JOINT, bool DEFER, class KA, class VA, class PF, class BF, class VF, class NM, class WS, class CB> ...
;     ...
;                     l += sum; m = mn;
;                     if (MODE == 0) pv_sub<DV / 32>(o, curv, VS, sub, s, r32, hi);
.LBB0_863:
	v_add_u32_e32 v50, v167, v164
	v_cvt_pk_bf16_f32 v88, v48, v1
	v_cvt_pk_bf16_f32 v89, v2, v49
	ds_read_b128 v[96:99], v50 offset:27712
	ds_read_b128 v[176:179], v50 offset:32320
	v_cvt_pk_bf16_f32 v90, v46, v47
	v_cvt_pk_bf16_f32 v91, v44, v45
	v_add_f32_e32 v103, 0, v48
	v_add_f32_e32 v103, v1, v103
	v_add_f32_e32 v103, v2, v103
	v_add_f32_e32 v103, v49, v103
	s_waitcnt lgkmcnt(1)
	v_mfma_f32_32x32x16_bf16 v[4:19], v[96:99], v[88:91], v[4:19]
	ds_read_b128 v[96:99], v50 offset:27744
	v_cvt_pk_bf16_f32 v92, v42, v43
	v_cvt_pk_bf16_f32 v93, v40, v41
	v_add_f32_e32 v103, v46, v103
	v_add_f32_e32 v103, v47, v103
	v_add_f32_e32 v103, v44, v103
	v_add_f32_e32 v103, v45, v103
	s_waitcnt lgkmcnt(1)
	v_mfma_f32_32x32x16_bf16 v[20:35], v[176:179], v[88:91], v[20:35]
	ds_read_b128 v[176:179], v50 offset:32352
	v_cvt_pk_bf16_f32 v94, v38, v39
	v_cvt_pk_bf16_f32 v95, v36, v37
	v_add_f32_e32 v103, v42, v103
	v_add_f32_e32 v103, v43, v103
	v_add_f32_e32 v103, v40, v103
	v_add_f32_e32 v103, v41, v103
	s_waitcnt lgkmcnt(1)
	v_mfma_f32_32x32x16_bf16 v[4:19], v[96:99], v[92:95], v[4:19]
	v_add_f32_e32 v103, v38, v103
	v_add_f32_e32 v103, v39, v103
	v_add_f32_e32 v103, v36, v103
	v_add_f32_e32 v103, v37, v103
	v_add_f32_e32 v221, v103, v221
	s_waitcnt lgkmcnt(0)
	v_mfma_f32_32x32x16_bf16 v[20:35], v[176:179], v[92:95], v[20:35]
	s_andn2_b64 vcc, exec, s[18:19]
	s_cbranch_vccnz .LBB0_794
	s_branch .LBB0_867
